# grid barrier: non-leader WGs poll the top-level generation word directly; per-XCD generation hop removed
# speedup vs baseline: 1.0014x; 1.0001x over previous
.LBB0_81:
	s_or_b64 exec, exec, s[10:11]
	v_cvt_f32_u32_e32 v4, v2
	s_waitcnt vmcnt(0)
	v_readfirstlane_b32 s3, v3
	v_sub_u32_e32 v3, 0, v2
	v_rcp_iflag_f32_e32 v4, v4
	v_add_u32_e32 v5, s3, v1
	v_mul_f32_e32 v4, 0x4f7ffffe, v4
	v_cvt_u32_f32_e32 v4, v4
	v_mul_lo_u32 v1, v3, v4
	v_mul_hi_u32 v1, v4, v1
	v_add_u32_e32 v1, v4, v1
	v_mul_hi_u32 v1, v5, v1
	v_mul_lo_u32 v3, v1, v2
	v_sub_u32_e32 v3, v5, v3
	v_add_u32_e32 v4, 1, v1
	v_cmp_ge_u32_e32 vcc, v3, v2
	s_nop 1
	v_cndmask_b32_e32 v1, v1, v4, vcc
	v_sub_u32_e32 v4, v3, v2
	v_cndmask_b32_e32 v3, v3, v4, vcc
	v_add_u32_e32 v4, 1, v1
	v_cmp_ge_u32_e32 vcc, v3, v2
	v_add_u32_e32 v3, 1, v5
	s_nop 0
	v_cndmask_b32_e32 v1, v1, v4, vcc
	v_mul_lo_u32 v4, v2, v1
	v_add_u32_e32 v2, v4, v2
	v_cmp_ne_u32_e32 vcc, v3, v2
	s_and_saveexec_b64 s[6:7], vcc
	s_xor_b64 s[6:7], exec, s[6:7]
	s_cbranch_execz .LBB0_95
	s_waitcnt lgkmcnt(0)
	v_mov_b32_e32 v0, 0x3100
	global_load_dword v0, v0, s[72:73] offset:1024 sc1
	s_add_u32 s12, s72, 0x3500
	s_addc_u32 s13, s73, 0
	s_waitcnt vmcnt(0)
	v_cmp_eq_u32_e32 vcc, v0, v1
	s_and_saveexec_b64 s[10:11], vcc
	s_cbranch_execz .LBB0_94
	s_mov_b32 s3, 1
	s_mov_b64 s[14:15], 0
	v_mov_b32_e32 v0, 0
	s_branch .LBB0_85

.LBB0_112:
	s_or_b64 exec, exec, s[6:7]
	s_mov_b64 s[6:7], exec
	v_mbcnt_lo_u32_b32 v0, s6, 0
	v_mbcnt_hi_u32_b32 v0, s7, v0
	v_cmp_eq_u32_e32 vcc, 0, v0
	s_waitcnt vmcnt(0)
	buffer_inv sc1
	s_and_saveexec_b64 s[10:11], vcc
	s_cbranch_execz .LBB0_114
	s_bcnt1_i32_b64 s3, s[6:7]
	v_mov_b32_e32 v0, 0x2000
	v_mov_b32_e32 v1, s3
.LBB0_114:
	s_or_b64 exec, exec, s[10:11]
	s_waitcnt vmcnt(0)

.LBB0_165:
	s_or_b64 exec, exec, s[18:19]
	v_cvt_f32_u32_e32 v4, v2
	s_waitcnt vmcnt(0)
	v_readfirstlane_b32 s3, v3
	v_sub_u32_e32 v3, 0, v2
	v_rcp_iflag_f32_e32 v4, v4
	v_add_u32_e32 v5, s3, v1
	v_mul_f32_e32 v4, 0x4f7ffffe, v4
	v_cvt_u32_f32_e32 v4, v4
	v_mul_lo_u32 v1, v3, v4
	v_mul_hi_u32 v1, v4, v1
	v_add_u32_e32 v1, v4, v1
	v_mul_hi_u32 v1, v5, v1
	v_mul_lo_u32 v3, v1, v2
	v_sub_u32_e32 v3, v5, v3
	v_add_u32_e32 v4, 1, v1
	v_cmp_ge_u32_e32 vcc, v3, v2
	s_nop 1
	v_cndmask_b32_e32 v1, v1, v4, vcc
	v_sub_u32_e32 v4, v3, v2
	v_cndmask_b32_e32 v3, v3, v4, vcc
	v_add_u32_e32 v4, 1, v1
	v_cmp_ge_u32_e32 vcc, v3, v2
	v_add_u32_e32 v3, 1, v5
	s_nop 0
	v_cndmask_b32_e32 v1, v1, v4, vcc
	v_mul_lo_u32 v4, v2, v1
	v_add_u32_e32 v2, v4, v2
	v_cmp_ne_u32_e32 vcc, v3, v2
	s_and_saveexec_b64 s[14:15], vcc
	s_xor_b64 s[14:15], exec, s[14:15]
	s_cbranch_execz .LBB0_179
	s_waitcnt lgkmcnt(0)
	v_mov_b32_e32 v0, 0x3100
	global_load_dword v0, v0, s[72:73] offset:1024 sc1
	s_add_u32 s22, s72, 0x3500
	s_addc_u32 s23, s73, 0
	s_waitcnt vmcnt(0)
	v_cmp_eq_u32_e32 vcc, v0, v1
	s_and_saveexec_b64 s[18:19], vcc
	s_cbranch_execz .LBB0_178
	s_mov_b32 s3, 1
	s_mov_b64 s[24:25], 0
	v_mov_b32_e32 v0, 0
	s_branch .LBB0_169

.LBB0_196:
	s_or_b64 exec, exec, s[14:15]
	s_mov_b64 s[14:15], exec
	v_mbcnt_lo_u32_b32 v0, s14, 0
	v_mbcnt_hi_u32_b32 v0, s15, v0
	v_cmp_eq_u32_e32 vcc, 0, v0
	s_waitcnt vmcnt(0)
	buffer_inv sc1
	s_and_saveexec_b64 s[18:19], vcc
	s_cbranch_execz .LBB0_198
	s_bcnt1_i32_b64 s3, s[14:15]
	v_mov_b32_e32 v0, 0x2000
	v_mov_b32_e32 v1, s3
.LBB0_198:
	s_or_b64 exec, exec, s[18:19]
	s_waitcnt vmcnt(0)

.LBB0_247:
	s_or_b64 exec, exec, s[22:23]
	v_cvt_f32_u32_e32 v4, v2
	s_waitcnt vmcnt(0)
	v_readfirstlane_b32 s3, v3
	v_sub_u32_e32 v3, 0, v2
	v_rcp_iflag_f32_e32 v4, v4
	v_add_u32_e32 v5, s3, v1
	v_mul_f32_e32 v4, 0x4f7ffffe, v4
	v_cvt_u32_f32_e32 v4, v4
	v_mul_lo_u32 v1, v3, v4
	v_mul_hi_u32 v1, v4, v1
	v_add_u32_e32 v1, v4, v1
	v_mul_hi_u32 v1, v5, v1
	v_mul_lo_u32 v3, v1, v2
	v_sub_u32_e32 v3, v5, v3
	v_add_u32_e32 v4, 1, v1
	v_cmp_ge_u32_e32 vcc, v3, v2
	s_nop 1
	v_cndmask_b32_e32 v1, v1, v4, vcc
	v_sub_u32_e32 v4, v3, v2
	v_cndmask_b32_e32 v3, v3, v4, vcc
	v_add_u32_e32 v4, 1, v1
	v_cmp_ge_u32_e32 vcc, v3, v2
	v_add_u32_e32 v3, 1, v5
	s_nop 0
	v_cndmask_b32_e32 v1, v1, v4, vcc
	v_mul_lo_u32 v4, v2, v1
	v_add_u32_e32 v2, v4, v2
	v_cmp_ne_u32_e32 vcc, v3, v2
	s_and_saveexec_b64 s[18:19], vcc
	s_xor_b64 s[18:19], exec, s[18:19]
	s_cbranch_execz .LBB0_261
	s_waitcnt lgkmcnt(0)
	v_mov_b32_e32 v0, 0x3100
	global_load_dword v0, v0, s[72:73] offset:1024 sc1
	s_add_u32 s24, s72, 0x3500
	s_addc_u32 s25, s73, 0
	s_waitcnt vmcnt(0)
	v_cmp_eq_u32_e32 vcc, v0, v1
	s_and_saveexec_b64 s[22:23], vcc
	s_cbranch_execz .LBB0_260
	s_mov_b32 s3, 1
	s_mov_b64 s[26:27], 0
	v_mov_b32_e32 v0, 0
	s_branch .LBB0_251

.LBB0_278:
	s_or_b64 exec, exec, s[18:19]
	s_mov_b64 s[18:19], exec
	v_mbcnt_lo_u32_b32 v0, s18, 0
	v_mbcnt_hi_u32_b32 v0, s19, v0
	v_cmp_eq_u32_e32 vcc, 0, v0
	s_waitcnt vmcnt(0)
	buffer_inv sc1
	s_and_saveexec_b64 s[22:23], vcc
	s_cbranch_execz .LBB0_280
	s_bcnt1_i32_b64 s3, s[18:19]
	v_mov_b32_e32 v0, 0x2000
	v_mov_b32_e32 v1, s3
.LBB0_280:
	s_or_b64 exec, exec, s[22:23]
	s_waitcnt vmcnt(0)

.LBB0_336:
	s_or_b64 exec, exec, s[18:19]
	s_mov_b64 s[18:19], exec
	v_mbcnt_lo_u32_b32 v0, s18, 0
	v_mbcnt_hi_u32_b32 v0, s19, v0
	v_cmp_eq_u32_e32 vcc, 0, v0
	s_waitcnt vmcnt(0)
	buffer_inv sc1
	s_and_saveexec_b64 s[22:23], vcc
	s_cbranch_execz .LBB0_338
	s_bcnt1_i32_b64 s3, s[18:19]
	v_mov_b32_e32 v0, 0x2000
	v_mov_b32_e32 v1, s3
.LBB0_338:
	s_or_b64 exec, exec, s[22:23]
	s_waitcnt vmcnt(0)

.LBB0_362:
	s_or_b64 exec, exec, s[16:17]
	v_cvt_f32_u32_e32 v4, v2
	s_waitcnt vmcnt(0)
	v_readfirstlane_b32 s3, v3
	v_sub_u32_e32 v3, 0, v2
	v_rcp_iflag_f32_e32 v4, v4
	v_add_u32_e32 v5, s3, v1
	v_mul_f32_e32 v4, 0x4f7ffffe, v4
	v_cvt_u32_f32_e32 v4, v4
	v_mul_lo_u32 v1, v3, v4
	v_mul_hi_u32 v1, v4, v1
	v_add_u32_e32 v1, v4, v1
	v_mul_hi_u32 v1, v5, v1
	v_mul_lo_u32 v3, v1, v2
	v_sub_u32_e32 v3, v5, v3
	v_add_u32_e32 v4, 1, v1
	v_cmp_ge_u32_e32 vcc, v3, v2
	s_nop 1
	v_cndmask_b32_e32 v1, v1, v4, vcc
	v_sub_u32_e32 v4, v3, v2
	v_cndmask_b32_e32 v3, v3, v4, vcc
	v_add_u32_e32 v4, 1, v1
	v_cmp_ge_u32_e32 vcc, v3, v2
	v_add_u32_e32 v3, 1, v5
	s_nop 0
	v_cndmask_b32_e32 v1, v1, v4, vcc
	v_mul_lo_u32 v4, v2, v1
	v_add_u32_e32 v2, v4, v2
	v_cmp_ne_u32_e32 vcc, v3, v2
	s_and_saveexec_b64 s[14:15], vcc
	s_xor_b64 s[14:15], exec, s[14:15]
	s_cbranch_execz .LBB0_376
	s_waitcnt lgkmcnt(0)
	v_mov_b32_e32 v0, 0x3100
	global_load_dword v0, v0, s[72:73] offset:1024 sc1
	s_add_u32 s18, s72, 0x3500
	s_addc_u32 s19, s73, 0
	s_waitcnt vmcnt(0)
	v_cmp_eq_u32_e32 vcc, v0, v1
	s_and_saveexec_b64 s[16:17], vcc
	s_cbranch_execz .LBB0_375
	s_mov_b32 s3, 1
	s_mov_b64 s[22:23], 0
	v_mov_b32_e32 v0, 0
	s_branch .LBB0_366

.LBB0_393:
	s_or_b64 exec, exec, s[14:15]
	s_mov_b64 s[14:15], exec
	v_mbcnt_lo_u32_b32 v0, s14, 0
	v_mbcnt_hi_u32_b32 v0, s15, v0
	v_cmp_eq_u32_e32 vcc, 0, v0
	s_waitcnt vmcnt(0)
	buffer_inv sc1
	s_and_saveexec_b64 s[16:17], vcc
	s_cbranch_execz .LBB0_395
	s_bcnt1_i32_b64 s3, s[14:15]
	v_mov_b32_e32 v0, 0x2000
	v_mov_b32_e32 v1, s3
.LBB0_395:
	s_or_b64 exec, exec, s[16:17]
	s_waitcnt vmcnt(0)

.LBB0_438:
	s_or_b64 exec, exec, s[16:17]
	v_cvt_f32_u32_e32 v4, v2
	s_waitcnt vmcnt(0)
	v_readfirstlane_b32 s3, v3
	v_sub_u32_e32 v3, 0, v2
	v_rcp_iflag_f32_e32 v4, v4
	v_add_u32_e32 v5, s3, v1
	v_mul_f32_e32 v4, 0x4f7ffffe, v4
	v_cvt_u32_f32_e32 v4, v4
	v_mul_lo_u32 v1, v3, v4
	v_mul_hi_u32 v1, v4, v1
	v_add_u32_e32 v1, v4, v1
	v_mul_hi_u32 v1, v5, v1
	v_mul_lo_u32 v3, v1, v2
	v_sub_u32_e32 v3, v5, v3
	v_add_u32_e32 v4, 1, v1
	v_cmp_ge_u32_e32 vcc, v3, v2
	s_nop 1
	v_cndmask_b32_e32 v1, v1, v4, vcc
	v_sub_u32_e32 v4, v3, v2
	v_cndmask_b32_e32 v3, v3, v4, vcc
	v_add_u32_e32 v4, 1, v1
	v_cmp_ge_u32_e32 vcc, v3, v2
	v_add_u32_e32 v3, 1, v5
	s_nop 0
	v_cndmask_b32_e32 v1, v1, v4, vcc
	v_mul_lo_u32 v4, v2, v1
	v_add_u32_e32 v2, v4, v2
	v_cmp_ne_u32_e32 vcc, v3, v2
	s_and_saveexec_b64 s[14:15], vcc
	s_xor_b64 s[14:15], exec, s[14:15]
	s_cbranch_execz .LBB0_452
	s_waitcnt lgkmcnt(0)
	v_mov_b32_e32 v0, 0x3100
	global_load_dword v0, v0, s[72:73] offset:1024 sc1
	s_add_u32 s18, s72, 0x3500
	s_addc_u32 s19, s73, 0
	s_waitcnt vmcnt(0)
	v_cmp_eq_u32_e32 vcc, v0, v1
	s_and_saveexec_b64 s[16:17], vcc
	s_cbranch_execz .LBB0_451
	s_mov_b32 s3, 1
	s_mov_b64 s[20:21], 0
	v_mov_b32_e32 v0, 0
	s_branch .LBB0_442

.LBB0_469:
	s_or_b64 exec, exec, s[14:15]
	s_mov_b64 s[14:15], exec
	v_mbcnt_lo_u32_b32 v0, s14, 0
	v_mbcnt_hi_u32_b32 v0, s15, v0
	v_cmp_eq_u32_e32 vcc, 0, v0
	s_waitcnt vmcnt(0)
	buffer_inv sc1
	s_and_saveexec_b64 s[16:17], vcc
	s_cbranch_execz .LBB0_471
	s_bcnt1_i32_b64 s3, s[14:15]
	v_mov_b32_e32 v0, 0x2000
	v_mov_b32_e32 v1, s3
.LBB0_471:
	s_or_b64 exec, exec, s[16:17]
	s_waitcnt vmcnt(0)

.LBB0_516:
	s_or_b64 exec, exec, s[14:15]
	v_cvt_f32_u32_e32 v4, v2
	s_waitcnt vmcnt(0)
	v_readfirstlane_b32 s3, v3
	v_sub_u32_e32 v3, 0, v2
	v_rcp_iflag_f32_e32 v4, v4
	v_add_u32_e32 v5, s3, v1
	v_mul_f32_e32 v4, 0x4f7ffffe, v4
	v_cvt_u32_f32_e32 v4, v4
	v_mul_lo_u32 v1, v3, v4
	v_mul_hi_u32 v1, v4, v1
	v_add_u32_e32 v1, v4, v1
	v_mul_hi_u32 v1, v5, v1
	v_mul_lo_u32 v3, v1, v2
	v_sub_u32_e32 v3, v5, v3
	v_add_u32_e32 v4, 1, v1
	v_cmp_ge_u32_e32 vcc, v3, v2
	s_nop 1
	v_cndmask_b32_e32 v1, v1, v4, vcc
	v_sub_u32_e32 v4, v3, v2
	v_cndmask_b32_e32 v3, v3, v4, vcc
	v_add_u32_e32 v4, 1, v1
	v_cmp_ge_u32_e32 vcc, v3, v2
	v_add_u32_e32 v3, 1, v5
	s_nop 0
	v_cndmask_b32_e32 v1, v1, v4, vcc
	v_mul_lo_u32 v4, v2, v1
	v_add_u32_e32 v2, v4, v2
	v_cmp_ne_u32_e32 vcc, v3, v2
	s_and_saveexec_b64 s[12:13], vcc
	s_xor_b64 s[12:13], exec, s[12:13]
	s_cbranch_execz .LBB0_530
	s_waitcnt lgkmcnt(0)
	v_mov_b32_e32 v0, 0x3100
	global_load_dword v0, v0, s[72:73] offset:1024 sc1
	s_add_u32 s16, s72, 0x3500
	s_addc_u32 s17, s73, 0
	s_waitcnt vmcnt(0)
	v_cmp_eq_u32_e32 vcc, v0, v1
	s_and_saveexec_b64 s[14:15], vcc
	s_cbranch_execz .LBB0_529
	s_mov_b32 s3, 1
	s_mov_b64 s[18:19], 0
	v_mov_b32_e32 v0, 0
	s_branch .LBB0_520

.LBB0_547:
	s_or_b64 exec, exec, s[12:13]
	s_mov_b64 s[12:13], exec
	v_mbcnt_lo_u32_b32 v0, s12, 0
	v_mbcnt_hi_u32_b32 v0, s13, v0
	v_cmp_eq_u32_e32 vcc, 0, v0
	s_waitcnt vmcnt(0)
	buffer_inv sc1
	s_and_saveexec_b64 s[14:15], vcc
	s_cbranch_execz .LBB0_549
	s_bcnt1_i32_b64 s3, s[12:13]
	v_mov_b32_e32 v0, 0x2000
	v_mov_b32_e32 v1, s3
.LBB0_549:
	s_or_b64 exec, exec, s[14:15]
	s_waitcnt vmcnt(0)

.LBB0_612:
	s_or_b64 exec, exec, s[10:11]
	v_cvt_f32_u32_e32 v4, v2
	s_waitcnt vmcnt(0)
	v_readfirstlane_b32 s3, v3
	v_sub_u32_e32 v3, 0, v2
	s_lshl_b32 s4, s33, 6
	v_rcp_iflag_f32_e32 v4, v4
	v_add_u32_e32 v5, s3, v1
	v_mul_f32_e32 v4, 0x4f7ffffe, v4
	v_cvt_u32_f32_e32 v4, v4
	v_mul_lo_u32 v1, v3, v4
	v_mul_hi_u32 v1, v4, v1
	v_add_u32_e32 v1, v4, v1
	v_mul_hi_u32 v1, v5, v1
	v_mul_lo_u32 v3, v1, v2
	v_sub_u32_e32 v3, v5, v3
	v_add_u32_e32 v4, 1, v1
	v_cmp_ge_u32_e32 vcc, v3, v2
	s_nop 1
	v_cndmask_b32_e32 v1, v1, v4, vcc
	v_sub_u32_e32 v4, v3, v2
	v_cndmask_b32_e32 v3, v3, v4, vcc
	v_add_u32_e32 v4, 1, v1
	v_cmp_ge_u32_e32 vcc, v3, v2
	v_add_u32_e32 v3, 1, v5
	s_nop 0
	v_cndmask_b32_e32 v1, v1, v4, vcc
	v_mul_lo_u32 v4, v2, v1
	v_add_u32_e32 v2, v4, v2
	v_cmp_ne_u32_e32 vcc, v3, v2
	s_and_saveexec_b64 s[8:9], vcc
	s_xor_b64 s[8:9], exec, s[8:9]
	s_cbranch_execz .LBB0_626
	s_waitcnt lgkmcnt(0)
	v_mov_b32_e32 v0, 0x3100
	global_load_dword v0, v0, s[72:73] offset:1024 sc1
	s_add_u32 s12, s72, 0x3500
	s_addc_u32 s13, s73, 0
	s_waitcnt vmcnt(0)
	v_cmp_eq_u32_e32 vcc, v0, v1
	s_and_saveexec_b64 s[10:11], vcc
	s_cbranch_execz .LBB0_625
	s_mov_b32 s3, 1
	s_mov_b64 s[14:15], 0
	v_mov_b32_e32 v0, 0
	s_branch .LBB0_616

.LBB0_643:
	s_or_b64 exec, exec, s[10:11]
	s_mov_b64 s[10:11], exec
	v_mbcnt_lo_u32_b32 v0, s10, 0
	v_mbcnt_hi_u32_b32 v0, s11, v0
	v_cmp_eq_u32_e32 vcc, 0, v0
	s_waitcnt vmcnt(0)
	buffer_inv sc1
	s_and_saveexec_b64 s[12:13], vcc
	s_cbranch_execz .LBB0_645
	s_bcnt1_i32_b64 s3, s[10:11]
	v_mov_b32_e32 v0, 0x2000
	v_mov_b32_e32 v1, s3
.LBB0_645:
	s_or_b64 exec, exec, s[12:13]
	s_waitcnt vmcnt(0)

.LBB0_648:
	s_or_b64 exec, exec, s[4:5]
	s_waitcnt vmcnt(0)
	buffer_inv sc1
	s_waitcnt vmcnt(0)

.LBB0_687:
	global_atomic_add v3, v[128:129], v149, off sc0
	v_cvt_f32_u32_e32 v1, v2
	v_sub_u32_e32 v4, 0, v2
	v_rcp_iflag_f32_e32 v1, v1
	s_nop 0
	v_mul_f32_e32 v1, 0x4f7ffffe, v1
	v_cvt_u32_f32_e32 v1, v1
	v_mul_lo_u32 v4, v4, v1
	v_mul_hi_u32 v4, v1, v4
	v_add_u32_e32 v1, v1, v4
	s_waitcnt vmcnt(0)
	v_mul_hi_u32 v1, v3, v1
	v_mul_lo_u32 v4, v1, v2
	v_sub_u32_e32 v4, v3, v4
	v_add_u32_e32 v5, 1, v1
	v_cmp_ge_u32_e32 vcc, v4, v2
	v_add_u32_e32 v3, 1, v3
	s_nop 0
	v_cndmask_b32_e32 v1, v1, v5, vcc
	v_sub_u32_e32 v5, v4, v2
	v_cndmask_b32_e32 v4, v4, v5, vcc
	v_add_u32_e32 v5, 1, v1
	v_cmp_ge_u32_e32 vcc, v4, v2
	s_nop 1
	v_cndmask_b32_e32 v1, v1, v5, vcc
	v_mul_lo_u32 v4, v2, v1
	v_add_u32_e32 v2, v4, v2
	v_cmp_ne_u32_e32 vcc, v3, v2
	s_and_saveexec_b64 s[6:7], vcc
	s_xor_b64 s[6:7], exec, s[6:7]
	s_cbranch_execz .LBB0_701
	s_waitcnt lgkmcnt(0)
	global_load_dword v0, v133, s[62:63] sc1
	s_waitcnt vmcnt(0)
	v_cmp_eq_u32_e32 vcc, v0, v1
	s_and_saveexec_b64 s[8:9], vcc
	s_cbranch_execz .LBB0_700
	s_mov_b32 s20, 1
	s_mov_b64 s[10:11], 0
	s_branch .LBB0_691

.LBB0_695:
	global_load_dword v0, v133, s[62:63] sc1
	s_add_i32 s20, s20, 1
	s_mov_b64 s[16:17], -1
	s_waitcnt vmcnt(0)
	v_cmp_ne_u32_e32 vcc, v0, v1
	s_orn2_b64 s[14:15], vcc, exec
	s_branch .LBB0_690

.LBB0_716:
	s_or_b64 exec, exec, s[6:7]
	s_and_saveexec_b64 s[6:7], s[8:9]
	s_cbranch_execz .LBB0_718
	global_atomic_add v[0:1], v149, off
.LBB0_718:
	s_or_b64 exec, exec, s[6:7]
	s_waitcnt vmcnt(0)
	buffer_inv sc1
	s_waitcnt vmcnt(0)
.LBB0_719:
	s_or_b64 exec, exec, s[4:5]
	s_lshl_b64 s[4:5], s[0:1], 10
	v_readlane_b32 s0, v243, 12
	s_waitcnt lgkmcnt(0)
	v_mov_b32_e32 v0, v165
	v_readlane_b32 s1, v243, 13
	s_barrier
	s_andn2_b64 vcc, exec, s[0:1]
	v_readfirstlane_b32 s6, v0
	s_cbranch_vccz .LBB0_721
	s_andn2_b64 vcc, exec, s[70:71]
	s_mov_b64 s[4:5], -1
	s_cbranch_vccnz .LBB0_650
	s_branch .LBB0_740

.LBB0_756:
	global_atomic_add v3, v[128:129], v149, off sc0
	v_cvt_f32_u32_e32 v1, v2
	v_sub_u32_e32 v4, 0, v2
	v_rcp_iflag_f32_e32 v1, v1
	s_nop 0
	v_mul_f32_e32 v1, 0x4f7ffffe, v1
	v_cvt_u32_f32_e32 v1, v1
	v_mul_lo_u32 v4, v4, v1
	v_mul_hi_u32 v4, v1, v4
	v_add_u32_e32 v1, v1, v4
	s_waitcnt vmcnt(0)
	v_mul_hi_u32 v1, v3, v1
	v_mul_lo_u32 v4, v1, v2
	v_sub_u32_e32 v4, v3, v4
	v_add_u32_e32 v5, 1, v1
	v_cmp_ge_u32_e32 vcc, v4, v2
	v_add_u32_e32 v3, 1, v3
	s_nop 0
	v_cndmask_b32_e32 v1, v1, v5, vcc
	v_sub_u32_e32 v5, v4, v2
	v_cndmask_b32_e32 v4, v4, v5, vcc
	v_add_u32_e32 v5, 1, v1
	v_cmp_ge_u32_e32 vcc, v4, v2
	s_nop 1
	v_cndmask_b32_e32 v1, v1, v5, vcc
	v_mul_lo_u32 v4, v2, v1
	v_add_u32_e32 v2, v4, v2
	v_cmp_ne_u32_e32 vcc, v3, v2
	s_and_saveexec_b64 s[4:5], vcc
	s_xor_b64 s[4:5], exec, s[4:5]
	s_cbranch_execz .LBB0_770
	s_waitcnt lgkmcnt(0)
	global_load_dword v0, v133, s[62:63] sc1
	s_waitcnt vmcnt(0)
	v_cmp_eq_u32_e32 vcc, v0, v1
	s_and_saveexec_b64 s[6:7], vcc
	s_cbranch_execz .LBB0_769
	s_mov_b32 s18, 1
	s_mov_b64 s[8:9], 0
	s_branch .LBB0_760

.LBB0_764:
	global_load_dword v0, v133, s[62:63] sc1
	s_add_i32 s18, s18, 1
	s_mov_b64 s[14:15], -1
	s_waitcnt vmcnt(0)
	v_cmp_ne_u32_e32 vcc, v0, v1
	s_orn2_b64 s[12:13], vcc, exec
	s_branch .LBB0_759
